# stack plus gmlp epilogue: all gain, bias and U loads issued once at the epilogue start instead of per piece after each store
# baseline (speedup 1.0000x reference)
; #define MFMA32(a, b, c) __builtin_amdgcn_mfma_f32_32x32x16_bf16((a), (b), (c), 0, 0, 0)
; __device__ __forceinline__ void gmlp_unit(const bf16* GVT, const bf16* U, const float* wsp, const float* bsp, const float* gain, bf16* OGM, int unit, LAS unsigned char* lds, int tid, int wave, int lane) {
;     ...
;     for (int ks = 0; ks < nks; ++ks) {
;         const bf16* apk = ap + (ks >> 1) * (256 * 32) + 16 * (ks & 1);
;         const bf16x8 a0 = *(const bf16x8*)apk, a1 = *(const bf16x8*)(apk + 32 * 32);
;         const int pb = 16 * ks + 8 * hh;
;         float rs[8];
; #pragma unroll
;         for (int j = 0; j < 8; ++j) rs[j] = rstd[pb + j];
; #pragma unroll
;         for (int nt = 0; nt < 2; ++nt) {
;             const int t = 64 * th + 32 * nt + r; const float* wq = wrow + (size_t)t * 128 + 16 * ks;
;             const f32x4 w0 = *(const f32x4*)wq, w1 = *(const f32x4*)(wq + 4); float bv[8];
; #pragma unroll
;             for (int j = 0; j < 4; ++j) { bv[j] = (pb + j <= t) ? w0[j] * rs[j] : 0.f; bv[4 + j] = (pb + 4 + j <= t) ? w1[j] * rs[4 + j] : 0.f; }
;             const bf16x8 bf = pack8(bv);
;             acc[0][nt] = MFMA32(a0, bf, acc[0][nt]); acc[1][nt] = MFMA32(a1, bf, acc[1][nt]);
;         }
;     }
.LBB0_105:
	s_add_i32 s94, s9, 0xffffd000
	v_lshl_add_u64 v[84:85], s[94:95], 1, v[112:113]
	s_sub_i32 s94, s12, 48
	v_lshl_add_u64 v[74:75], s[94:95], 2, v[92:93]
	v_lshl_add_u64 v[72:73], v[74:75], 0, v[178:179]
	global_load_dwordx4 v[64:67], v[84:85], off
	global_load_dwordx4 v[68:71], v[84:85], off offset:2048
	ds_read_b128 v[76:79], v119
	ds_read_b128 v[80:83], v119 offset:16
	global_load_dwordx4 v[122:125], v[72:73], off offset:16
	global_load_dwordx4 v[126:129], v[72:73], off
	v_add_u32_e32 v120, s12, v116
	v_subrev_u32_e32 v114, 48, v120
	v_cmp_le_u32_e64 s[6:7], v114, v94
	s_add_i32 s94, s9, 0xfffff000
	s_mov_b32 s13, s95
	s_add_i32 s15, s15, -4
	s_waitcnt vmcnt(0) lgkmcnt(1)
	v_mul_f32_e32 v111, v76, v126
	v_cndmask_b32_e64 v111, 0, v111, s[6:7]
	v_cmp_lt_u32_e64 s[6:7], v114, v94
	v_mul_f32_e32 v115, v77, v127
	v_or_b32_e32 v127, 4, v114
	v_cndmask_b32_e64 v115, 0, v115, s[6:7]
	v_cvt_pk_bf16_f32 v130, v111, v115
	v_mov_b32_e32 v111, v179
	v_lshl_add_u64 v[74:75], v[74:75], 0, v[110:111]
	global_load_dwordx4 v[134:137], v[74:75], off offset:16
	global_load_dwordx4 v[138:141], v[74:75], off
	v_cmp_le_u32_e64 s[6:7], v114, v96
	v_or_b32_e32 v126, 5, v114
	s_waitcnt vmcnt(0)
	v_mul_f32_e32 v76, v76, v138
	v_cndmask_b32_e64 v115, 0, v76, s[6:7]
	v_cmp_lt_u32_e64 s[6:7], v114, v96
	v_mul_f32_e32 v76, v77, v139
	s_nop 0
	v_cndmask_b32_e64 v121, 0, v76, s[6:7]
	s_waitcnt lgkmcnt(0)
	v_pk_mul_f32 v[76:77], v[80:81], v[122:123]
	v_cmp_le_u32_e64 s[6:7], v127, v94
	v_cvt_pk_bf16_f32 v76, v76, v77
	v_or_b32_e32 v123, 2, v114
	v_cndmask_b32_e64 v77, 0, v76, s[6:7]
	v_cmp_le_u32_e64 s[6:7], v126, v89
	v_lshrrev_b32_e32 v76, 16, v76
	v_or_b32_e32 v122, 3, v114
	v_cndmask_b32_e64 v76, 0, v76, s[6:7]
	v_perm_b32 v132, v76, v77, s52
	v_pk_mul_f32 v[76:77], v[78:79], v[128:129]
	v_cmp_le_u32_e64 s[6:7], v123, v94
	v_cvt_pk_bf16_f32 v76, v76, v77
	v_or_b32_e32 v128, 7, v114
	v_cndmask_b32_e64 v77, 0, v76, s[6:7]
	v_lshrrev_b32_e32 v76, 16, v76
	v_cmp_le_u32_e64 s[6:7], v122, v89
	v_or_b32_e32 v114, 6, v114
	v_pk_mul_f32 v[78:79], v[78:79], v[140:141]
	v_cndmask_b32_e64 v76, 0, v76, s[6:7]
	v_perm_b32 v131, v76, v77, s52
	v_pk_mul_f32 v[76:77], v[82:83], v[124:125]
	v_cmp_le_u32_e64 s[6:7], v114, v94
	v_cvt_pk_bf16_f32 v76, v76, v77
	v_pk_mul_f32 v[80:81], v[80:81], v[134:135]
	v_cndmask_b32_e64 v77, 0, v76, s[6:7]
	v_lshrrev_b32_e32 v76, 16, v76
	v_cmp_le_u32_e64 s[6:7], v128, v89
	v_pk_mul_f32 v[82:83], v[82:83], v[136:137]
	s_nop 0
	v_cndmask_b32_e64 v76, 0, v76, s[6:7]
	v_perm_b32 v133, v76, v77, s52
	v_cvt_pk_bf16_f32 v77, v78, v79
	v_cmp_le_u32_e64 s[6:7], v123, v96
	v_cvt_pk_bf16_f32 v76, v115, v121
	v_mfma_f32_32x32x16_bf16 v[48:63], v[64:67], v[130:133], v[48:63]
	v_cndmask_b32_e64 v78, 0, v77, s[6:7]
	v_lshrrev_b32_e32 v77, 16, v77
	v_cmp_le_u32_e64 s[6:7], v122, v87
	s_nop 1
	v_cndmask_b32_e64 v77, 0, v77, s[6:7]
	v_perm_b32 v77, v77, v78, s52
	v_cvt_pk_bf16_f32 v78, v80, v81
	v_cmp_le_u32_e64 s[6:7], v127, v96
	v_mfma_f32_32x32x16_bf16 v[16:31], v[68:71], v[130:133], v[16:31]
	s_nop 0
	v_cndmask_b32_e64 v79, 0, v78, s[6:7]
	v_cmp_le_u32_e64 s[6:7], v126, v87
	v_lshrrev_b32_e32 v78, 16, v78
	s_nop 0
	v_cndmask_b32_e64 v78, 0, v78, s[6:7]
	v_perm_b32 v78, v78, v79, s52
	v_cvt_pk_bf16_f32 v79, v82, v83
	v_cmp_le_u32_e64 s[6:7], v114, v96
	s_nop 1
	v_cndmask_b32_e64 v80, 0, v79, s[6:7]
	v_lshrrev_b32_e32 v79, 16, v79
	v_cmp_le_u32_e64 s[6:7], v128, v87
	s_nop 1
	v_cndmask_b32_e64 v79, 0, v79, s[6:7]
	v_perm_b32 v79, v79, v80, s52
	s_nop 1
	v_mfma_f32_32x32x16_bf16 v[32:47], v[64:67], v[76:79], v[32:47]
	v_mfma_f32_32x32x16_bf16 v[0:15], v[68:71], v[76:79], v[0:15]
	global_load_dwordx4 v[64:67], v[84:85], off offset:32
	global_load_dwordx4 v[68:71], v[84:85], off offset:2080
	ds_read_b128 v[76:79], v119 offset:64
	global_load_dwordx4 v[80:83], v[72:73], off offset:80
	global_load_dwordx4 v[122:125], v[72:73], off offset:64
	global_load_dwordx4 v[126:129], v[74:75], off offset:80
	global_load_dwordx4 v[130:133], v[74:75], off offset:64
	v_subrev_u32_e32 v84, 32, v120
	ds_read_b128 v[134:137], v119 offset:80
	v_cmp_le_u32_e64 s[6:7], v84, v94
	v_or_b32_e32 v121, 4, v84
	v_or_b32_e32 v115, 5, v84
	s_waitcnt vmcnt(3) lgkmcnt(0)
	v_pk_mul_f32 v[74:75], v[134:135], v[80:81]
	s_waitcnt vmcnt(2)
	v_mul_f32_e32 v72, v76, v122
	v_cndmask_b32_e64 v72, 0, v72, s[6:7]
	v_cmp_lt_u32_e64 s[6:7], v84, v94
	v_mul_f32_e32 v73, v77, v123
	v_or_b32_e32 v123, 2, v84
	v_cndmask_b32_e64 v73, 0, v73, s[6:7]
	v_cvt_pk_bf16_f32 v72, v72, v73
	s_waitcnt vmcnt(0)
; #define MFMA32(a, b, c) __builtin_amdgcn_mfma_f32_32x32x16_bf16((a), (b), (c), 0, 0, 0)
; __device__ __forceinline__ void gmlp_unit(const bf16* GVT, const bf16* U, const float* wsp, const float* bsp, const float* gain, bf16* OGM, int unit, LAS unsigned char* lds, int tid, int wave, int lane) {
;     ...
;     for (int ks = 0; ks < nks; ++ks) {
;         const bf16* apk = ap + (ks >> 1) * (256 * 32) + 16 * (ks & 1);
;         const bf16x8 a0 = *(const bf16x8*)apk, a1 = *(const bf16x8*)(apk + 32 * 32);
;         const int pb = 16 * ks + 8 * hh;
;         float rs[8];
; #pragma unroll
;         for (int j = 0; j < 8; ++j) rs[j] = rstd[pb + j];
; #pragma unroll
;         for (int nt = 0; nt < 2; ++nt) {
;             const int t = 64 * th + 32 * nt + r; const float* wq = wrow + (size_t)t * 128 + 16 * ks;
;             const f32x4 w0 = *(const f32x4*)wq, w1 = *(const f32x4*)(wq + 4); float bv[8];
; #pragma unroll
;             for (int j = 0; j < 4; ++j) { bv[j] = (pb + j <= t) ? w0[j] * rs[j] : 0.f; bv[4 + j] = (pb + 4 + j <= t) ? w1[j] * rs[4 + j] : 0.f; }
;             const bf16x8 bf = pack8(bv);
;             acc[0][nt] = MFMA32(a0, bf, acc[0][nt]); acc[1][nt] = MFMA32(a1, bf, acc[1][nt]);
;         }
;     }
	v_mul_f32_e32 v73, v76, v130
	v_cmp_le_u32_e64 s[6:7], v84, v96
	v_pk_mul_f32 v[80:81], v[78:79], v[124:125]
	v_or_b32_e32 v122, 3, v84
	v_cndmask_b32_e64 v85, 0, v73, s[6:7]
	v_cmp_lt_u32_e64 s[6:7], v84, v96
	v_mul_f32_e32 v73, v77, v131
	v_or_b32_e32 v124, 7, v84
	v_cndmask_b32_e64 v114, 0, v73, s[6:7]
	v_cvt_pk_bf16_f32 v73, v74, v75
	v_cmp_le_u32_e64 s[6:7], v121, v94
	v_or_b32_e32 v84, 6, v84
	v_pk_mul_f32 v[78:79], v[78:79], v[132:133]
	v_cndmask_b32_e64 v74, 0, v73, s[6:7]
	v_cmp_le_u32_e64 s[6:7], v115, v89
	v_lshrrev_b32_e32 v73, 16, v73
	v_pk_mul_f32 v[76:77], v[134:135], v[126:127]
	v_cndmask_b32_e64 v73, 0, v73, s[6:7]
	v_perm_b32 v74, v73, v74, s52
	v_cvt_pk_bf16_f32 v73, v80, v81
	v_cmp_le_u32_e64 s[6:7], v123, v94
	v_pk_mul_f32 v[80:81], v[136:137], v[82:83]
	s_nop 0
	v_cndmask_b32_e64 v75, 0, v73, s[6:7]
	v_lshrrev_b32_e32 v73, 16, v73
	v_cmp_le_u32_e64 s[6:7], v122, v89
	s_nop 1
	v_cndmask_b32_e64 v73, 0, v73, s[6:7]
	v_perm_b32 v73, v73, v75, s52
	v_cvt_pk_bf16_f32 v75, v80, v81
	v_cmp_le_u32_e64 s[6:7], v84, v94
	s_nop 1
	v_cndmask_b32_e64 v80, 0, v75, s[6:7]
	v_lshrrev_b32_e32 v75, 16, v75
	v_cmp_le_u32_e64 s[6:7], v124, v89
	s_nop 1
	v_cndmask_b32_e64 v75, 0, v75, s[6:7]
	v_perm_b32 v75, v75, v80, s52
	v_cmp_le_u32_e64 s[6:7], v123, v96
	v_pk_mul_f32 v[80:81], v[136:137], v[128:129]
	v_mfma_f32_32x32x16_bf16 v[48:63], v[64:67], v[72:75], v[48:63]
	v_mfma_f32_32x32x16_bf16 v[16:31], v[68:71], v[72:75], v[16:31]
	v_cvt_pk_bf16_f32 v73, v78, v79
	v_cndmask_b32_e64 v74, 0, v73, s[6:7]
	v_lshrrev_b32_e32 v73, 16, v73
	v_cmp_le_u32_e64 s[6:7], v122, v87
	v_cvt_pk_bf16_f32 v72, v85, v114
	v_add_u32_e32 v114, -16, v120
	v_cndmask_b32_e64 v73, 0, v73, s[6:7]
	v_perm_b32 v73, v73, v74, s52
	v_cvt_pk_bf16_f32 v74, v76, v77
	v_cmp_le_u32_e64 s[6:7], v121, v96
	v_or_b32_e32 v121, 2, v114
	s_nop 0
	v_cndmask_b32_e64 v75, 0, v74, s[6:7]
	v_cmp_le_u32_e64 s[6:7], v115, v87
	v_lshrrev_b32_e32 v74, 16, v74
	v_or_b32_e32 v115, 3, v114
	v_cndmask_b32_e64 v74, 0, v74, s[6:7]
	v_perm_b32 v74, v74, v75, s52
	v_cvt_pk_bf16_f32 v75, v80, v81
	v_cmp_le_u32_e64 s[6:7], v84, v96
	s_nop 1
	v_cndmask_b32_e64 v76, 0, v75, s[6:7]
	v_lshrrev_b32_e32 v75, 16, v75
	v_cmp_le_u32_e64 s[6:7], v124, v87
	s_nop 1
	v_cndmask_b32_e64 v75, 0, v75, s[6:7]
	v_perm_b32 v75, v75, v76, s52
	v_cmp_le_u32_e64 s[6:7], v114, v94
	s_nop 0
	v_mfma_f32_32x32x16_bf16 v[0:15], v[68:71], v[72:75], v[0:15]
	v_lshl_add_u64 v[68:69], s[94:95], 1, v[112:113]
	s_add_i32 s94, s12, -16
	v_lshl_add_u64 v[84:85], s[94:95], 2, v[92:93]
	v_lshl_add_u64 v[80:81], v[84:85], 0, v[178:179]
	v_mfma_f32_32x32x16_bf16 v[32:47], v[64:67], v[72:75], v[32:47]
	global_load_dwordx4 v[64:67], v[68:69], off
	s_nop 0
	global_load_dwordx4 v[68:71], v[68:69], off offset:2048
	ds_read_b128 v[72:75], v119 offset:128
	global_load_dwordx4 v[76:79], v[80:81], off offset:16
	s_nop 0
	global_load_dwordx4 v[80:83], v[80:81], off
	s_waitcnt vmcnt(0) lgkmcnt(0)
	v_mul_f32_e32 v80, v72, v80
	v_cndmask_b32_e64 v80, 0, v80, s[6:7]
	v_cmp_lt_u32_e64 s[6:7], v114, v94
	v_mul_f32_e32 v81, v73, v81
	s_nop 0
	v_cndmask_b32_e64 v81, 0, v81, s[6:7]
	v_cvt_pk_bf16_f32 v122, v80, v81
	v_lshl_add_u64 v[80:81], v[84:85], 0, v[110:111]
	global_load_dwordx4 v[126:129], v[80:81], off offset:16
	global_load_dwordx4 v[130:133], v[80:81], off
	ds_read_b128 v[134:137], v119 offset:144
	v_cmp_le_u32_e64 s[6:7], v114, v96
	v_or_b32_e32 v85, 4, v114
	v_or_b32_e32 v84, 5, v114
	s_waitcnt vmcnt(0)
	v_mul_f32_e32 v72, v72, v130
	v_cndmask_b32_e64 v80, 0, v72, s[6:7]
	v_cmp_lt_u32_e64 s[6:7], v114, v96
	v_mul_f32_e32 v72, v73, v131
	s_nop 0
	v_cndmask_b32_e64 v81, 0, v72, s[6:7]
	s_waitcnt lgkmcnt(0)
	v_pk_mul_f32 v[72:73], v[134:135], v[76:77]
	v_cmp_le_u32_e64 s[6:7], v85, v94
	v_cvt_pk_bf16_f32 v72, v72, v73
	v_pk_mul_f32 v[76:77], v[134:135], v[126:127]
	v_cndmask_b32_e64 v73, 0, v72, s[6:7]
	v_cmp_le_u32_e64 s[6:7], v84, v89
	v_lshrrev_b32_e32 v72, 16, v72
	s_nop 0
	v_cndmask_b32_e64 v72, 0, v72, s[6:7]
	v_perm_b32 v124, v72, v73, s52
	v_pk_mul_f32 v[72:73], v[74:75], v[82:83]
	v_cmp_le_u32_e64 s[6:7], v121, v94
	v_cvt_pk_bf16_f32 v72, v72, v73
	v_or_b32_e32 v83, 6, v114
	v_cndmask_b32_e64 v73, 0, v72, s[6:7]
	v_lshrrev_b32_e32 v72, 16, v72
	v_cmp_le_u32_e64 s[6:7], v115, v89
	v_or_b32_e32 v82, 7, v114
	v_pk_mul_f32 v[74:75], v[74:75], v[132:133]
	v_cndmask_b32_e64 v72, 0, v72, s[6:7]
	v_perm_b32 v123, v72, v73, s52
	v_pk_mul_f32 v[72:73], v[136:137], v[78:79]
	v_cmp_le_u32_e64 s[6:7], v83, v94
	v_cvt_pk_bf16_f32 v72, v72, v73
	v_pk_mul_f32 v[78:79], v[136:137], v[128:129]
	v_cndmask_b32_e64 v73, 0, v72, s[6:7]
	v_lshrrev_b32_e32 v72, 16, v72
	v_cmp_le_u32_e64 s[6:7], v82, v89
	s_nop 1
	v_cndmask_b32_e64 v72, 0, v72, s[6:7]
	v_perm_b32 v125, v72, v73, s52
	v_cvt_pk_bf16_f32 v73, v74, v75
	v_cmp_le_u32_e64 s[6:7], v121, v96
	v_cvt_pk_bf16_f32 v72, v80, v81
	v_mfma_f32_32x32x16_bf16 v[48:63], v[64:67], v[122:125], v[48:63]
	v_cndmask_b32_e64 v74, 0, v73, s[6:7]
	v_lshrrev_b32_e32 v73, 16, v73
	v_cmp_le_u32_e64 s[6:7], v115, v87
	v_or_b32_e32 v121, 5, v120
	s_nop 0
	v_cndmask_b32_e64 v73, 0, v73, s[6:7]
	v_perm_b32 v73, v73, v74, s52
	v_cvt_pk_bf16_f32 v74, v76, v77
	v_cmp_le_u32_e64 s[6:7], v85, v96
	v_mfma_f32_32x32x16_bf16 v[16:31], v[68:71], v[122:125], v[16:31]
	s_nop 0
	v_cndmask_b32_e64 v75, 0, v74, s[6:7]
	v_cmp_le_u32_e64 s[6:7], v84, v87
	v_lshrrev_b32_e32 v74, 16, v74
	s_nop 0
	v_cndmask_b32_e64 v74, 0, v74, s[6:7]
	v_perm_b32 v74, v74, v75, s52
	v_cvt_pk_bf16_f32 v75, v78, v79
	v_cmp_le_u32_e64 s[6:7], v83, v96
	s_nop 1
	v_cndmask_b32_e64 v76, 0, v75, s[6:7]
	v_lshrrev_b32_e32 v75, 16, v75
	v_cmp_le_u32_e64 s[6:7], v82, v87
	s_nop 1
	v_cndmask_b32_e64 v75, 0, v75, s[6:7]
	v_perm_b32 v75, v75, v76, s52
	s_and_b32 s6, s9, 0x7fffe000
	s_lshl_b32 s94, s6, 1
	v_mfma_f32_32x32x16_bf16 v[32:47], v[64:67], v[72:75], v[32:47]
	v_lshl_add_u64 v[64:65], v[112:113], 0, s[94:95]
	v_cmp_le_u32_e64 s[6:7], v120, v94
	s_addk_i32 s9, 0x4000
	v_mfma_f32_32x32x16_bf16 v[0:15], v[68:71], v[72:75], v[0:15]
	v_lshl_add_u64 v[72:73], s[12:13], 2, v[92:93]
	v_lshl_add_u64 v[74:75], v[72:73], 0, v[178:179]
	global_load_dwordx4 v[68:71], v[64:65], off offset:32
	s_nop 0
	global_load_dwordx4 v[64:67], v[64:65], off offset:2080
	ds_read_b128 v[122:125], v119 offset:192
	global_load_dwordx4 v[78:81], v[74:75], off offset:16
	global_load_dwordx4 v[126:129], v[74:75], off
	v_lshl_add_u64 v[82:83], v[72:73], 0, v[110:111]
	v_or_b32_e32 v111, 7, v120
	s_add_i32 s12, s12, 64
	s_cmp_lg_u32 s15, 0
	s_waitcnt vmcnt(0) lgkmcnt(0)
; #define MFMA32(a, b, c) __builtin_amdgcn_mfma_f32_32x32x16_bf16((a), (b), (c), 0, 0, 0)
; __device__ __forceinline__ void gmlp_unit(const bf16* GVT, const bf16* U, const float* wsp, const float* bsp, const float* gain, bf16* OGM, int unit, LAS unsigned char* lds, int tid, int wave, int lane) {
;     ...
;     for (int ks = 0; ks < nks; ++ks) {
;         const bf16* apk = ap + (ks >> 1) * (256 * 32) + 16 * (ks & 1);
;         const bf16x8 a0 = *(const bf16x8*)apk, a1 = *(const bf16x8*)(apk + 32 * 32);
;         const int pb = 16 * ks + 8 * hh;
;         float rs[8];
; #pragma unroll
;         for (int j = 0; j < 8; ++j) rs[j] = rstd[pb + j];
; #pragma unroll
;         for (int nt = 0; nt < 2; ++nt) {
;             const int t = 64 * th + 32 * nt + r; const float* wq = wrow + (size_t)t * 128 + 16 * ks;
;             const f32x4 w0 = *(const f32x4*)wq, w1 = *(const f32x4*)(wq + 4); float bv[8];
; #pragma unroll
;             for (int j = 0; j < 4; ++j) { bv[j] = (pb + j <= t) ? w0[j] * rs[j] : 0.f; bv[4 + j] = (pb + 4 + j <= t) ? w1[j] * rs[4 + j] : 0.f; }
;             const bf16x8 bf = pack8(bv);
;             acc[0][nt] = MFMA32(a0, bf, acc[0][nt]); acc[1][nt] = MFMA32(a1, bf, acc[1][nt]);
;         }
;     }
; #pragma unroll
;     for (int mt = 0; mt < 2; ++mt)
; #pragma unroll
;         for (int nt = 0; nt < 2; ++nt) {
;             const int t = 64 * th + 32 * nt + r; const float bias = bsp[g * 128 + t];
; #pragma unroll
;             for (int gp = 0; gp < 2; ++gp) {
;                 v2u pc[2];
; #pragma unroll
;                 for (int e = 0; e < 2; ++e) { const int q4 = 2 * gp + e;
;                     const int c = g * 64 + mt * 32 + 8 * q4 + 4 * hh;
;                     const f32x4 gn = *(const f32x4*)(gain + c);
;                     const v2u uw = *(const v2u*)(U + (tok0 + t) * 256 + c);
;                     const float v0 = (acc[mt][nt][4 * q4] * gn.x + bias) * bf_lo(uw.x), v1 = (acc[mt][nt][4 * q4 + 1] * gn.y + bias) * bf_hi(uw.x);
;                     const float v2 = (acc[mt][nt][4 * q4 + 2] * gn.z + bias) * bf_lo(uw.y), v3 = (acc[mt][nt][4 * q4 + 3] * gn.w + bias) * bf_hi(uw.y);
;                     pc[e].x = pk2(v0, v1); pc[e].y = pk2(v2, v3); }
;                 *(v4u*)(OGM + (tok0 + t) * 256 + g * 64 + mt * 32 + 8 * (2 * gp + hh)) = pair_widen(pc[0], pc[1], hh);
	v_mul_f32_e32 v74, v122, v126
	v_cndmask_b32_e64 v74, 0, v74, s[6:7]
	v_cmp_lt_u32_e64 s[6:7], v120, v94
	v_mul_f32_e32 v75, v123, v127
	v_or_b32_e32 v127, 3, v120
	v_cndmask_b32_e64 v75, 0, v75, s[6:7]
	v_cvt_pk_bf16_f32 v76, v74, v75
	global_load_dwordx4 v[72:75], v[82:83], off offset:16
	global_load_dwordx4 v[130:133], v[82:83], off
	ds_read_b128 v[82:85], v119 offset:208
	v_cmp_le_u32_e64 s[6:7], v120, v96
	v_add_u32_e32 v119, 0x100, v119
	s_waitcnt lgkmcnt(0)
	v_pk_mul_f32 v[78:79], v[82:83], v[78:79]
	s_waitcnt vmcnt(1)
	v_pk_mul_f32 v[82:83], v[82:83], v[72:73]
	s_waitcnt vmcnt(0)
	v_mul_f32_e32 v77, v122, v130
	v_cndmask_b32_e64 v126, 0, v77, s[6:7]
	v_cmp_lt_u32_e64 s[6:7], v120, v96
	v_mul_f32_e32 v77, v123, v131
	v_or_b32_e32 v122, 4, v120
	v_cndmask_b32_e64 v123, 0, v77, s[6:7]
	v_cvt_pk_bf16_f32 v77, v78, v79
	v_cmp_le_u32_e64 s[6:7], v122, v94
	v_or_b32_e32 v130, 2, v120
	v_pk_mul_f32 v[72:73], v[124:125], v[128:129]
	v_cndmask_b32_e64 v78, 0, v77, s[6:7]
	v_cmp_le_u32_e64 s[6:7], v121, v89
	v_lshrrev_b32_e32 v77, 16, v77
	v_cvt_pk_bf16_f32 v72, v72, v73
	v_cndmask_b32_e64 v77, 0, v77, s[6:7]
	v_cmp_le_u32_e64 s[6:7], v130, v94
	v_perm_b32 v78, v77, v78, s52
	v_or_b32_e32 v120, 6, v120
	v_cndmask_b32_e64 v73, 0, v72, s[6:7]
	v_lshrrev_b32_e32 v72, 16, v72
	v_cmp_le_u32_e64 s[6:7], v127, v89
	v_pk_mul_f32 v[114:115], v[124:125], v[132:133]
	s_nop 0
	v_cndmask_b32_e64 v72, 0, v72, s[6:7]
	v_perm_b32 v77, v72, v73, s52
	v_pk_mul_f32 v[72:73], v[84:85], v[80:81]
	v_cmp_le_u32_e64 s[6:7], v120, v94
	v_cvt_pk_bf16_f32 v72, v72, v73
	s_nop 0
	v_cndmask_b32_e64 v73, 0, v72, s[6:7]
	v_lshrrev_b32_e32 v72, 16, v72
	v_cmp_le_u32_e64 s[6:7], v111, v89
	s_nop 1
	v_cndmask_b32_e64 v72, 0, v72, s[6:7]
	v_perm_b32 v79, v72, v73, s52
	v_cvt_pk_bf16_f32 v73, v114, v115
	v_cmp_le_u32_e64 s[6:7], v130, v96
	v_mfma_f32_32x32x16_bf16 v[48:63], v[68:71], v[76:79], v[48:63]
	v_cvt_pk_bf16_f32 v72, v126, v123
	v_mfma_f32_32x32x16_bf16 v[16:31], v[64:67], v[76:79], v[16:31]
	v_mul_f32_e64 v76, v84, v74
	v_mul_f32_e64 v77, v85, v75
	v_cndmask_b32_e64 v74, 0, v73, s[6:7]
	v_lshrrev_b32_e32 v73, 16, v73
	v_cmp_le_u32_e64 s[6:7], v127, v87
	s_nop 1
	v_cndmask_b32_e64 v73, 0, v73, s[6:7]
	v_perm_b32 v73, v73, v74, s52
	v_cvt_pk_bf16_f32 v74, v82, v83
	v_cmp_le_u32_e64 s[6:7], v122, v96
	s_nop 1
	v_cndmask_b32_e64 v75, 0, v74, s[6:7]
	v_cmp_le_u32_e64 s[6:7], v121, v87
	v_lshrrev_b32_e32 v74, 16, v74
	s_nop 0
	v_cndmask_b32_e64 v74, 0, v74, s[6:7]
	v_perm_b32 v74, v74, v75, s52
	v_cvt_pk_bf16_f32 v75, v76, v77
	v_cmp_le_u32_e64 s[6:7], v120, v96
	s_nop 1
	v_cndmask_b32_e64 v76, 0, v75, s[6:7]
	v_lshrrev_b32_e32 v75, 16, v75
	v_cmp_le_u32_e64 s[6:7], v111, v87
	s_nop 1
	v_cndmask_b32_e64 v75, 0, v75, s[6:7]
	v_perm_b32 v75, v75, v76, s52
	s_nop 1
	v_mfma_f32_32x32x16_bf16 v[32:47], v[68:71], v[72:75], v[32:47]
	v_mfma_f32_32x32x16_bf16 v[0:15], v[64:67], v[72:75], v[0:15]
	s_cbranch_scc1 .LBB0_105
	v_mov_b32_e32 v65, s11
	v_or_b32_e32 v64, s10, v94
	v_lshlrev_b64 v[76:77], 9, v[64:65]
	v_lshl_add_u64 v[64:65], v[106:107], 0, v[76:77]
	v_mov_b32_e32 v249, s11
	v_or_b32_e32 v248, s10, v96
	v_lshlrev_b64 v[248:249], 9, v[248:249]
	v_lshl_add_u64 v[182:183], v[106:107], 0, v[248:249]
	global_load_dwordx4 v[192:195], v[98:99], off
	global_load_dwordx4 v[196:199], v[98:99], off offset:32
	global_load_dwordx4 v[200:203], v[98:99], off offset:64
	global_load_dwordx4 v[204:207], v[98:99], off offset:96
	global_load_dwordx4 v[208:211], v[98:99], off offset:128
	global_load_dwordx4 v[212:215], v[98:99], off offset:160
	global_load_dwordx4 v[216:219], v[98:99], off offset:192
	global_load_dwordx4 v[220:223], v[98:99], off offset:224
	global_load_dword v180, v[100:101], off
	global_load_dword v181, v[102:103], off offset:128
	global_load_dwordx2 v[148:149], v[64:65], off
	global_load_dwordx2 v[150:151], v[64:65], off offset:16
	global_load_dwordx2 v[152:153], v[64:65], off offset:32
	global_load_dwordx2 v[154:155], v[64:65], off offset:48
	global_load_dwordx2 v[156:157], v[64:65], off offset:64
	global_load_dwordx2 v[158:159], v[64:65], off offset:80
	global_load_dwordx2 v[160:161], v[64:65], off offset:96
	global_load_dwordx2 v[162:163], v[64:65], off offset:112
	global_load_dwordx2 v[232:233], v[182:183], off
	global_load_dwordx2 v[234:235], v[182:183], off offset:16
	global_load_dwordx2 v[236:237], v[182:183], off offset:32
	global_load_dwordx2 v[238:239], v[182:183], off offset:48
	global_load_dwordx2 v[240:241], v[182:183], off offset:64
	global_load_dwordx2 v[242:243], v[182:183], off offset:80
	global_load_dwordx2 v[244:245], v[182:183], off offset:96
	global_load_dwordx2 v[246:247], v[182:183], off offset:112
	s_waitcnt vmcnt(0)
	s_nop 1
	v_mov_b32_e32 v74, v180
	s_nop 1
	v_mov_b32_e32 v66, v192
	v_mov_b32_e32 v67, v193
	v_mov_b32_e32 v68, v194
	v_mov_b32_e32 v69, v195
	s_nop 1
	v_mov_b32_e32 v70, v196
	v_mov_b32_e32 v71, v197
	v_mov_b32_e32 v72, v198
	v_mov_b32_e32 v73, v199
	s_nop 1
	v_mov_b32_e32 v78, v148
	v_mov_b32_e32 v79, v149
	s_nop 1
	v_mov_b32_e32 v80, v150
	v_mov_b32_e32 v81, v151
	s_add_i32 s8, s8, s82
	s_cmpk_gt_i32 s8, 0xff
	v_pk_fma_f32 v[50:51], v[50:51], v[68:69], v[74:75] op_sel_hi:[1,1,0]
	v_pk_fma_f32 v[54:55], v[54:55], v[72:73], v[74:75] op_sel_hi:[1,1,0]
	v_lshlrev_b32_e32 v68, 16, v79
	v_and_b32_e32 v69, 0xffff0000, v79
	v_lshlrev_b32_e32 v72, 16, v81
	v_and_b32_e32 v73, 0xffff0000, v81
	v_pk_fma_f32 v[48:49], v[48:49], v[66:67], v[74:75] op_sel_hi:[1,1,0]
	v_pk_fma_f32 v[52:53], v[52:53], v[70:71], v[74:75] op_sel_hi:[1,1,0]
	v_lshlrev_b32_e32 v66, 16, v78
	v_and_b32_e32 v67, 0xffff0000, v78
	v_lshlrev_b32_e32 v70, 16, v80
	v_and_b32_e32 v71, 0xffff0000, v80
	v_pk_mul_f32 v[50:51], v[50:51], v[68:69]
	v_pk_mul_f32 v[54:55], v[54:55], v[72:73]
	v_pk_mul_f32 v[48:49], v[48:49], v[66:67]
	v_pk_mul_f32 v[52:53], v[52:53], v[70:71]
	v_cvt_pk_bf16_f32 v50, v50, v51
	v_cvt_pk_bf16_f32 v51, v54, v55
	v_cvt_pk_bf16_f32 v66, v48, v49
	v_cvt_pk_bf16_f32 v52, v52, v53
	v_cndmask_b32_e64 v48, v50, v51, s[4:5]
	ds_bpermute_b32 v54, v117, v48
	v_cndmask_b32_e64 v48, v66, v52, s[4:5]
	ds_bpermute_b32 v55, v117, v48
	v_lshl_add_u64 v[48:49], v[108:109], 0, v[76:77]
	v_mov_b32_e32 v73, s11
	s_waitcnt lgkmcnt(1)
; __device__ __forceinline__ unsigned pk2(float lo, float hi) { f32v2 v = {lo, hi}; bf16v2 r = __builtin_convertvector(v, bf16v2); return __builtin_bit_cast(unsigned, r); }
; __device__ __forceinline__ void gmlp_unit(const bf16* GVT, const bf16* U, const float* wsp, const float* bsp, const float* gain, bf16* OGM, int unit, LAS unsigned char* lds, int tid, int wave, int lane) {
;     ...
;     for (int mt = 0; mt < 2; ++mt)
; #pragma unroll
;         for (int nt = 0; nt < 2; ++nt) {
;             const int t = 64 * th + 32 * nt + r; const float bias = bsp[g * 128 + t];
; #pragma unroll
;             for (int gp = 0; gp < 2; ++gp) {
;                 v2u pc[2];
; #pragma unroll
;                 for (int e = 0; e < 2; ++e) { const int q4 = 2 * gp + e;
;                     const int c = g * 64 + mt * 32 + 8 * q4 + 4 * hh;
;                     const f32x4 gn = *(const f32x4*)(gain + c);
;                     const v2u uw = *(const v2u*)(U + (tok0 + t) * 256 + c);
;                     const float v0 = (acc[mt][nt][4 * q4] * gn.x + bias) * bf_lo(uw.x), v1 = (acc[mt][nt][4 * q4 + 1] * gn.y + bias) * bf_hi(uw.x);
;                     const float v2 = (acc[mt][nt][4 * q4 + 2] * gn.z + bias) * bf_lo(uw.y), v3 = (acc[mt][nt][4 * q4 + 3] * gn.w + bias) * bf_hi(uw.y);
;                     pc[e].x = pk2(v0, v1); pc[e].y = pk2(v2, v3); }
;                 *(v4u*)(OGM + (tok0 + t) * 256 + g * 64 + mt * 32 + 8 * (2 * gp + hh)) = pair_widen(pc[0], pc[1], hh);
	v_cndmask_b32_e64 v53, v51, v54, s[4:5]
	v_cndmask_b32_e64 v51, v54, v50, s[4:5]
	s_waitcnt lgkmcnt(0)
	v_cndmask_b32_e64 v52, v52, v55, s[4:5]
	v_cndmask_b32_e64 v50, v55, v66, s[4:5]
	global_store_dwordx4 v[48:49], v[50:53], off
	s_nop 1
	v_mov_b32_e32 v50, v200
	v_mov_b32_e32 v51, v201
	v_mov_b32_e32 v52, v202
	v_mov_b32_e32 v53, v203
	s_nop 0
	s_nop 1
	v_mov_b32_e32 v54, v152
	v_mov_b32_e32 v55, v153
	s_nop 1
	v_mov_b32_e32 v66, v204
	v_mov_b32_e32 v67, v205
	v_mov_b32_e32 v68, v206
	v_mov_b32_e32 v69, v207
	s_nop 1
	v_mov_b32_e32 v70, v154
	v_mov_b32_e32 v71, v155
	v_or_b32_e32 v72, s10, v96
	v_pk_fma_f32 v[50:51], v[56:57], v[50:51], v[74:75] op_sel_hi:[1,1,0]
	v_lshlrev_b32_e32 v56, 16, v54
	v_and_b32_e32 v57, 0xffff0000, v54
	v_pk_fma_f32 v[52:53], v[58:59], v[52:53], v[74:75] op_sel_hi:[1,1,0]
	v_lshlrev_b32_e32 v54, 16, v55
	v_and_b32_e32 v55, 0xffff0000, v55
	v_pk_fma_f32 v[58:59], v[60:61], v[66:67], v[74:75] op_sel_hi:[1,1,0]
	v_pk_fma_f32 v[62:63], v[62:63], v[68:69], v[74:75] op_sel_hi:[1,1,0]
	v_lshlrev_b32_e32 v66, 16, v71
	v_and_b32_e32 v67, 0xffff0000, v71
	v_lshlrev_b32_e32 v60, 16, v70
	v_and_b32_e32 v61, 0xffff0000, v70
	v_pk_mul_f32 v[50:51], v[50:51], v[56:57]
	v_pk_mul_f32 v[52:53], v[52:53], v[54:55]
	v_pk_mul_f32 v[56:57], v[62:63], v[66:67]
	v_pk_mul_f32 v[54:55], v[58:59], v[60:61]
	v_cvt_pk_bf16_f32 v52, v52, v53
	v_cvt_pk_bf16_f32 v53, v56, v57
	v_cvt_pk_bf16_f32 v58, v50, v51
	v_cvt_pk_bf16_f32 v54, v54, v55
	v_cndmask_b32_e64 v50, v52, v53, s[4:5]
	ds_bpermute_b32 v56, v117, v50
	v_cndmask_b32_e64 v50, v58, v54, s[4:5]
	ds_bpermute_b32 v57, v117, v50
	v_lshlrev_b64 v[60:61], 9, v[72:73]
	v_lshl_add_u64 v[50:51], v[106:107], 0, v[60:61]
	s_waitcnt lgkmcnt(1)
	v_cndmask_b32_e64 v55, v53, v56, s[4:5]
	v_cndmask_b32_e64 v53, v56, v52, s[4:5]
	s_waitcnt lgkmcnt(0)
	v_cndmask_b32_e64 v54, v54, v57, s[4:5]
	v_cndmask_b32_e64 v52, v57, v58, s[4:5]
	global_store_dwordx4 v[48:49], v[52:55], off offset:32
	s_nop 1
	v_mov_b32_e32 v62, v181
	s_nop 0
	s_nop 1
	v_mov_b32_e32 v52, v192
	v_mov_b32_e32 v53, v193
	v_mov_b32_e32 v54, v194
	v_mov_b32_e32 v55, v195
	s_nop 1
	v_mov_b32_e32 v66, v232
	v_mov_b32_e32 v67, v233
	s_nop 1
	v_mov_b32_e32 v56, v196
	v_mov_b32_e32 v57, v197
	v_mov_b32_e32 v58, v198
	v_mov_b32_e32 v59, v199
	s_nop 1
	v_mov_b32_e32 v68, v234
	v_mov_b32_e32 v69, v235
	v_pk_fma_f32 v[34:35], v[34:35], v[54:55], v[62:63] op_sel_hi:[1,1,0]
	v_lshlrev_b32_e32 v54, 16, v67
	v_and_b32_e32 v55, 0xffff0000, v67
	v_pk_fma_f32 v[38:39], v[38:39], v[58:59], v[62:63] op_sel_hi:[1,1,0]
	v_lshlrev_b32_e32 v58, 16, v69
	v_and_b32_e32 v59, 0xffff0000, v69
	v_pk_fma_f32 v[32:33], v[32:33], v[52:53], v[62:63] op_sel_hi:[1,1,0]
	v_lshlrev_b32_e32 v52, 16, v66
	v_and_b32_e32 v53, 0xffff0000, v66
	v_pk_fma_f32 v[36:37], v[36:37], v[56:57], v[62:63] op_sel_hi:[1,1,0]
	v_lshlrev_b32_e32 v56, 16, v68
	v_and_b32_e32 v57, 0xffff0000, v68
	v_pk_mul_f32 v[34:35], v[34:35], v[54:55]
	v_pk_mul_f32 v[38:39], v[38:39], v[58:59]
	v_pk_mul_f32 v[32:33], v[32:33], v[52:53]
	v_pk_mul_f32 v[36:37], v[36:37], v[56:57]
	v_cvt_pk_bf16_f32 v34, v34, v35
	v_cvt_pk_bf16_f32 v35, v38, v39
	v_cvt_pk_bf16_f32 v52, v32, v33
	v_cvt_pk_bf16_f32 v36, v36, v37
	v_cndmask_b32_e64 v32, v34, v35, s[4:5]
	ds_bpermute_b32 v38, v117, v32
	v_cndmask_b32_e64 v32, v52, v36, s[4:5]
	ds_bpermute_b32 v39, v117, v32
	v_lshl_add_u64 v[32:33], v[108:109], 0, v[60:61]
	s_waitcnt lgkmcnt(1)
	v_cndmask_b32_e64 v37, v35, v38, s[4:5]
	v_cndmask_b32_e64 v35, v38, v34, s[4:5]
	s_waitcnt lgkmcnt(0)
	v_cndmask_b32_e64 v36, v36, v39, s[4:5]
	v_cndmask_b32_e64 v34, v39, v52, s[4:5]
	global_store_dwordx4 v[32:33], v[34:37], off
	s_nop 1
	v_mov_b32_e32 v34, v200
	v_mov_b32_e32 v35, v201
	v_mov_b32_e32 v36, v202
	v_mov_b32_e32 v37, v203
	s_nop 0
	s_nop 1
	v_mov_b32_e32 v38, v236
	v_mov_b32_e32 v39, v237
	s_nop 1
	v_mov_b32_e32 v52, v204
	v_mov_b32_e32 v53, v205
	v_mov_b32_e32 v54, v206
	v_mov_b32_e32 v55, v207
	s_nop 1
	v_mov_b32_e32 v56, v238
	v_mov_b32_e32 v57, v239
	v_pk_fma_f32 v[34:35], v[40:41], v[34:35], v[62:63] op_sel_hi:[1,1,0]
	v_lshlrev_b32_e32 v40, 16, v38
	v_and_b32_e32 v41, 0xffff0000, v38
	v_pk_fma_f32 v[36:37], v[42:43], v[36:37], v[62:63] op_sel_hi:[1,1,0]
	v_lshlrev_b32_e32 v38, 16, v39
	v_and_b32_e32 v39, 0xffff0000, v39
	v_pk_fma_f32 v[42:43], v[44:45], v[52:53], v[62:63] op_sel_hi:[1,1,0]
	v_lshlrev_b32_e32 v44, 16, v56
	v_and_b32_e32 v45, 0xffff0000, v56
	v_pk_fma_f32 v[46:47], v[46:47], v[54:55], v[62:63] op_sel_hi:[1,1,0]
	v_lshlrev_b32_e32 v52, 16, v57
	v_and_b32_e32 v53, 0xffff0000, v57
	v_pk_mul_f32 v[34:35], v[34:35], v[40:41]
	v_pk_mul_f32 v[36:37], v[36:37], v[38:39]
	v_pk_mul_f32 v[38:39], v[42:43], v[44:45]
	v_pk_mul_f32 v[40:41], v[46:47], v[52:53]
	v_cvt_pk_bf16_f32 v34, v34, v35
	v_cvt_pk_bf16_f32 v35, v36, v37
	v_cvt_pk_bf16_f32 v36, v38, v39
	v_cvt_pk_bf16_f32 v37, v40, v41
	v_cndmask_b32_e64 v38, v35, v37, s[4:5]
	v_cndmask_b32_e64 v39, v34, v36, s[4:5]
	ds_bpermute_b32 v38, v117, v38
	ds_bpermute_b32 v39, v117, v39
	s_waitcnt lgkmcnt(1)
	v_cndmask_b32_e64 v37, v37, v38, s[4:5]
	v_cndmask_b32_e64 v35, v38, v35, s[4:5]
	s_waitcnt lgkmcnt(0)
; __device__ __forceinline__ unsigned pk2(float lo, float hi) { f32v2 v = {lo, hi}; bf16v2 r = __builtin_convertvector(v, bf16v2); return __builtin_bit_cast(unsigned, r); }
; __device__ __forceinline__ void gmlp_unit(const bf16* GVT, const bf16* U, const float* wsp, const float* bsp, const float* gain, bf16* OGM, int unit, LAS unsigned char* lds, int tid, int wave, int lane) {
;     ...
;     for (int mt = 0; mt < 2; ++mt)
; #pragma unroll
;         for (int nt = 0; nt < 2; ++nt) {
;             const int t = 64 * th + 32 * nt + r; const float bias = bsp[g * 128 + t];
; #pragma unroll
;             for (int gp = 0; gp < 2; ++gp) {
;                 v2u pc[2];
; #pragma unroll
;                 for (int e = 0; e < 2; ++e) { const int q4 = 2 * gp + e;
;                     const int c = g * 64 + mt * 32 + 8 * q4 + 4 * hh;
;                     const f32x4 gn = *(const f32x4*)(gain + c);
;                     const v2u uw = *(const v2u*)(U + (tok0 + t) * 256 + c);
;                     const float v0 = (acc[mt][nt][4 * q4] * gn.x + bias) * bf_lo(uw.x), v1 = (acc[mt][nt][4 * q4 + 1] * gn.y + bias) * bf_hi(uw.x);
;                     const float v2 = (acc[mt][nt][4 * q4 + 2] * gn.z + bias) * bf_lo(uw.y), v3 = (acc[mt][nt][4 * q4 + 3] * gn.w + bias) * bf_hi(uw.y);
;                     pc[e].x = pk2(v0, v1); pc[e].y = pk2(v2, v3); }
;                 *(v4u*)(OGM + (tok0 + t) * 256 + g * 64 + mt * 32 + 8 * (2 * gp + hh)) = pair_widen(pc[0], pc[1], hh);
;             }
;         }
;     __syncthreads();
; __global__ void __launch_bounds__(NTHREADS, 2) fwd_megakernel(Args A) {
;     ...
;             for (int u = blockIdx.x; u < NTOK / 128; u += G)
	v_cndmask_b32_e64 v36, v36, v39, s[4:5]
	v_cndmask_b32_e64 v34, v39, v34, s[4:5]
	global_store_dwordx4 v[32:33], v[34:37], off offset:32
	s_nop 1
	v_mov_b32_e32 v42, v180
	s_nop 0
	s_nop 1
	v_mov_b32_e32 v34, v208
	v_mov_b32_e32 v35, v209
	v_mov_b32_e32 v36, v210
	v_mov_b32_e32 v37, v211
	s_nop 1
	v_mov_b32_e32 v44, v156
	v_mov_b32_e32 v45, v157
	s_nop 1
	v_mov_b32_e32 v38, v212
	v_mov_b32_e32 v39, v213
	v_mov_b32_e32 v40, v214
	v_mov_b32_e32 v41, v215
	s_nop 1
	v_mov_b32_e32 v46, v158
	v_mov_b32_e32 v47, v159
	v_pk_fma_f32 v[16:17], v[16:17], v[34:35], v[42:43] op_sel_hi:[1,1,0]
	v_lshlrev_b32_e32 v34, 16, v44
	v_and_b32_e32 v35, 0xffff0000, v44
	v_pk_fma_f32 v[18:19], v[18:19], v[36:37], v[42:43] op_sel_hi:[1,1,0]
	v_lshlrev_b32_e32 v36, 16, v45
	v_and_b32_e32 v37, 0xffff0000, v45
	v_pk_fma_f32 v[20:21], v[20:21], v[38:39], v[42:43] op_sel_hi:[1,1,0]
	v_lshlrev_b32_e32 v38, 16, v46
	v_and_b32_e32 v39, 0xffff0000, v46
	v_pk_fma_f32 v[22:23], v[22:23], v[40:41], v[42:43] op_sel_hi:[1,1,0]
	v_lshlrev_b32_e32 v40, 16, v47
	v_and_b32_e32 v41, 0xffff0000, v47
	v_pk_mul_f32 v[16:17], v[16:17], v[34:35]
	v_pk_mul_f32 v[18:19], v[18:19], v[36:37]
	v_pk_mul_f32 v[20:21], v[20:21], v[38:39]
	v_pk_mul_f32 v[22:23], v[22:23], v[40:41]
	v_cvt_pk_bf16_f32 v16, v16, v17
	v_cvt_pk_bf16_f32 v17, v18, v19
	v_cvt_pk_bf16_f32 v18, v20, v21
	v_cvt_pk_bf16_f32 v19, v22, v23
	v_cndmask_b32_e64 v20, v17, v19, s[4:5]
	v_cndmask_b32_e64 v21, v16, v18, s[4:5]
	ds_bpermute_b32 v20, v117, v20
	ds_bpermute_b32 v21, v117, v21
	s_waitcnt lgkmcnt(1)
	v_cndmask_b32_e64 v19, v19, v20, s[4:5]
	v_cndmask_b32_e64 v17, v20, v17, s[4:5]
	s_waitcnt lgkmcnt(0)
	v_cndmask_b32_e64 v18, v18, v21, s[4:5]
	v_cndmask_b32_e64 v16, v21, v16, s[4:5]
	global_store_dwordx4 v[48:49], v[16:19], off offset:64
	s_nop 1
	v_mov_b32_e32 v16, v216
	v_mov_b32_e32 v17, v217
	v_mov_b32_e32 v18, v218
	v_mov_b32_e32 v19, v219
	s_nop 0
	s_nop 1
	v_mov_b32_e32 v34, v160
	v_mov_b32_e32 v35, v161
	s_nop 1
	v_mov_b32_e32 v20, v220
	v_mov_b32_e32 v21, v221
	v_mov_b32_e32 v22, v222
	v_mov_b32_e32 v23, v223
	s_nop 1
	v_mov_b32_e32 v36, v162
	v_mov_b32_e32 v37, v163
	v_pk_fma_f32 v[16:17], v[24:25], v[16:17], v[42:43] op_sel_hi:[1,1,0]
	v_lshlrev_b32_e32 v24, 16, v34
	v_and_b32_e32 v25, 0xffff0000, v34
	v_pk_fma_f32 v[18:19], v[26:27], v[18:19], v[42:43] op_sel_hi:[1,1,0]
	v_lshlrev_b32_e32 v26, 16, v35
	v_and_b32_e32 v27, 0xffff0000, v35
	v_pk_fma_f32 v[20:21], v[28:29], v[20:21], v[42:43] op_sel_hi:[1,1,0]
	v_lshlrev_b32_e32 v28, 16, v36
	v_and_b32_e32 v29, 0xffff0000, v36
	v_pk_fma_f32 v[22:23], v[30:31], v[22:23], v[42:43] op_sel_hi:[1,1,0]
	v_lshlrev_b32_e32 v30, 16, v37
	v_and_b32_e32 v31, 0xffff0000, v37
	v_pk_mul_f32 v[16:17], v[16:17], v[24:25]
	v_pk_mul_f32 v[18:19], v[18:19], v[26:27]
	v_pk_mul_f32 v[20:21], v[20:21], v[28:29]
	v_pk_mul_f32 v[22:23], v[22:23], v[30:31]
	v_cvt_pk_bf16_f32 v16, v16, v17
	v_cvt_pk_bf16_f32 v17, v18, v19
	v_cvt_pk_bf16_f32 v18, v20, v21
	v_cvt_pk_bf16_f32 v19, v22, v23
	v_cndmask_b32_e64 v20, v17, v19, s[4:5]
	v_cndmask_b32_e64 v21, v16, v18, s[4:5]
	ds_bpermute_b32 v20, v117, v20
	ds_bpermute_b32 v21, v117, v21
	s_waitcnt lgkmcnt(1)
	v_cndmask_b32_e64 v19, v19, v20, s[4:5]
	v_cndmask_b32_e64 v17, v20, v17, s[4:5]
	s_waitcnt lgkmcnt(0)
	v_cndmask_b32_e64 v18, v18, v21, s[4:5]
	v_cndmask_b32_e64 v16, v21, v16, s[4:5]
	global_store_dwordx4 v[48:49], v[16:19], off offset:96
	s_nop 1
	v_mov_b32_e32 v24, v181
	s_nop 0
	s_nop 1
	v_mov_b32_e32 v16, v208
	v_mov_b32_e32 v17, v209
	v_mov_b32_e32 v18, v210
	v_mov_b32_e32 v19, v211
	s_nop 1
	v_mov_b32_e32 v26, v240
	v_mov_b32_e32 v27, v241
	s_nop 1
	v_mov_b32_e32 v20, v212
	v_mov_b32_e32 v21, v213
	v_mov_b32_e32 v22, v214
	v_mov_b32_e32 v23, v215
	s_nop 1
	v_mov_b32_e32 v28, v242
	v_mov_b32_e32 v29, v243
	v_pk_fma_f32 v[0:1], v[0:1], v[16:17], v[24:25] op_sel_hi:[1,1,0]
	v_lshlrev_b32_e32 v16, 16, v26
	v_and_b32_e32 v17, 0xffff0000, v26
	v_pk_fma_f32 v[2:3], v[2:3], v[18:19], v[24:25] op_sel_hi:[1,1,0]
	v_lshlrev_b32_e32 v18, 16, v27
	v_and_b32_e32 v19, 0xffff0000, v27
	v_pk_fma_f32 v[4:5], v[4:5], v[20:21], v[24:25] op_sel_hi:[1,1,0]
	v_lshlrev_b32_e32 v20, 16, v28
	v_and_b32_e32 v21, 0xffff0000, v28
	v_pk_fma_f32 v[6:7], v[6:7], v[22:23], v[24:25] op_sel_hi:[1,1,0]
	v_lshlrev_b32_e32 v22, 16, v29
	v_and_b32_e32 v23, 0xffff0000, v29
	v_pk_mul_f32 v[0:1], v[0:1], v[16:17]
	v_pk_mul_f32 v[2:3], v[2:3], v[18:19]
	v_pk_mul_f32 v[4:5], v[4:5], v[20:21]
	v_pk_mul_f32 v[6:7], v[6:7], v[22:23]
	v_cvt_pk_bf16_f32 v0, v0, v1
	v_cvt_pk_bf16_f32 v1, v2, v3
	v_cvt_pk_bf16_f32 v2, v4, v5
	v_cvt_pk_bf16_f32 v3, v6, v7
	v_cndmask_b32_e64 v4, v1, v3, s[4:5]
	v_cndmask_b32_e64 v5, v0, v2, s[4:5]
	ds_bpermute_b32 v4, v117, v4
	ds_bpermute_b32 v5, v117, v5
	s_waitcnt lgkmcnt(1)
	v_cndmask_b32_e64 v3, v3, v4, s[4:5]
	v_cndmask_b32_e64 v1, v4, v1, s[4:5]
	s_waitcnt lgkmcnt(0)
	v_cndmask_b32_e64 v2, v2, v5, s[4:5]
	v_cndmask_b32_e64 v0, v5, v0, s[4:5]
	global_store_dwordx4 v[32:33], v[0:3], off offset:64
	s_nop 1
	v_mov_b32_e32 v0, v216
	v_mov_b32_e32 v1, v217
	v_mov_b32_e32 v2, v218
	v_mov_b32_e32 v3, v219
	s_nop 0
	s_nop 1
	v_mov_b32_e32 v16, v244
	v_mov_b32_e32 v17, v245
	s_nop 1
	v_mov_b32_e32 v4, v220
	v_mov_b32_e32 v5, v221
	v_mov_b32_e32 v6, v222
	v_mov_b32_e32 v7, v223
	s_nop 1
	v_mov_b32_e32 v18, v246
	v_mov_b32_e32 v19, v247
	v_pk_fma_f32 v[0:1], v[8:9], v[0:1], v[24:25] op_sel_hi:[1,1,0]
	v_lshlrev_b32_e32 v8, 16, v16
	v_and_b32_e32 v9, 0xffff0000, v16
	v_pk_fma_f32 v[2:3], v[10:11], v[2:3], v[24:25] op_sel_hi:[1,1,0]
	v_lshlrev_b32_e32 v10, 16, v17
	v_and_b32_e32 v11, 0xffff0000, v17
	v_pk_fma_f32 v[4:5], v[12:13], v[4:5], v[24:25] op_sel_hi:[1,1,0]
	v_lshlrev_b32_e32 v12, 16, v18
	v_and_b32_e32 v13, 0xffff0000, v18
	v_pk_fma_f32 v[6:7], v[14:15], v[6:7], v[24:25] op_sel_hi:[1,1,0]
	v_lshlrev_b32_e32 v14, 16, v19
	v_and_b32_e32 v15, 0xffff0000, v19
	v_pk_mul_f32 v[0:1], v[0:1], v[8:9]
	v_pk_mul_f32 v[2:3], v[2:3], v[10:11]
	v_pk_mul_f32 v[4:5], v[4:5], v[12:13]
	v_pk_mul_f32 v[6:7], v[6:7], v[14:15]
	v_cvt_pk_bf16_f32 v0, v0, v1
	v_cvt_pk_bf16_f32 v1, v2, v3
	v_cvt_pk_bf16_f32 v2, v4, v5
	v_cvt_pk_bf16_f32 v3, v6, v7
	v_cndmask_b32_e64 v4, v1, v3, s[4:5]
	v_cndmask_b32_e64 v5, v0, v2, s[4:5]
	ds_bpermute_b32 v4, v117, v4
	ds_bpermute_b32 v5, v117, v5
	s_waitcnt lgkmcnt(1)
	v_cndmask_b32_e64 v3, v3, v4, s[4:5]
	v_cndmask_b32_e64 v1, v4, v1, s[4:5]
	s_waitcnt lgkmcnt(0)
	v_cndmask_b32_e64 v2, v2, v5, s[4:5]
	v_cndmask_b32_e64 v0, v5, v0, s[4:5]
	global_store_dwordx4 v[32:33], v[0:3], off offset:96
	s_barrier
	s_cbranch_scc0 .LBB0_102
